# adds specialised next-unit tile coordinates (11 SALU instead of the generic division sequence) to v023
# speedup vs baseline: 1.0098x; 1.0025x over previous
.LBB0_208:
	s_lshr_b32 s99, s91, 2
	s_cmp_eq_u32 s99, 1
	s_cselect_b32 s98, 12, 0x7fffffff
	s_add_i32 s84, s84, 1
	s_mul_i32 s4, s84, s56
	s_mul_hi_u32 s5, s84, s57
	s_add_i32 s5, s5, s4
	s_mul_i32 s4, s84, s57
	s_add_u32 s42, s4, s2
	s_addc_u32 s43, s5, s3
	v_cmp_gt_i64_e32 vcc, s[42:43], v[150:151]
	v_cmp_lt_i64_e64 s[4:5], s[42:43], v[148:149]
	s_cbranch_vccnz .LBB0_210
	s_and_b32 s100, s42, 7
	s_mul_i32 s100, s100, 0xc0
	s_lshr_b32 s101, s42, 3
	s_add_i32 s100, s100, s101
	s_mul_hi_u32 s101, s100, 0x2aaaaab
	s_mul_i32 s28, s101, 0x60
	s_sub_i32 s28, s100, s28
	s_and_b32 s100, s28, 7
	s_lshl_b32 s40, s101, 3
	s_add_i32 s40, s40, s100
	s_lshr_b32 s28, s28, 3
	s_mov_b32 s85, s84

.LBB0_379:
	s_lshr_b32 s99, s91, 2
	s_cmp_eq_u32 s99, 1
	s_cselect_b32 s98, 12, 0x7fffffff
	s_add_i32 s84, s84, 1
	s_mul_i32 s6, s84, s67
	s_mul_hi_u32 s7, s84, s79
	s_add_i32 s7, s7, s6
	s_mul_i32 s6, s84, s79
	s_add_u32 s40, s6, s2
	s_addc_u32 s41, s7, s81
	v_cmp_gt_i64_e32 vcc, s[40:41], v[146:147]
	v_cmp_lt_i64_e64 s[6:7], s[40:41], v[144:145]
	s_cbranch_vccnz .LBB0_385
	s_and_b32 s100, s40, 7
	s_mul_i32 s100, s100, 0x40
	s_lshr_b32 s101, s40, 3
	s_add_i32 s100, s100, s101
	s_mul_hi_u32 s101, s100, 0x8000000
	s_mul_i32 s26, s101, 0x20
	s_sub_i32 s26, s100, s26
	s_and_b32 s100, s26, 7
	s_lshl_b32 s28, s101, 3
	s_add_i32 s28, s28, s100
	s_lshr_b32 s26, s26, 3

.LBB0_473:
	s_lshr_b32 s99, s91, 2
	s_cmp_eq_u32 s99, 1
	s_cselect_b32 s98, 12, 0x7fffffff
	s_add_i32 s77, s77, 1
	s_mul_i32 s4, s77, s52
	s_mul_hi_u32 s5, s77, s53
	s_add_i32 s5, s5, s4
	s_mul_i32 s4, s77, s53
	s_add_u32 s26, s4, s2
	s_addc_u32 s27, s5, s3
	v_cmp_gt_i64_e32 vcc, s[26:27], v[146:147]
	v_cmp_lt_i64_e64 s[4:5], s[26:27], v[144:145]
	s_cbranch_vccnz .LBB0_475
	s_and_b32 s100, s26, 7
	s_mul_i32 s100, s100, 0x160
	s_lshr_b32 s101, s26, 3
	s_add_i32 s100, s100, s101
	s_mul_hi_u32 s101, s100, 0x1745d18
	s_mul_i32 s10, s101, 0xb0
	s_sub_i32 s10, s100, s10
	s_and_b32 s100, s10, 7
	s_lshl_b32 s22, s101, 3
	s_add_i32 s22, s22, s100
	s_lshr_b32 s10, s10, 3
	s_mov_b32 s79, s77

.LBB0_551:
	s_lshr_b32 s99, s91, 2
	s_cmp_eq_u32 s99, 1
	s_cselect_b32 s98, 40, 0x7fffffff
	s_add_i32 s66, s66, 1
	s_mul_i32 s0, s66, s59
	s_mul_hi_u32 s1, s66, s62
	s_add_i32 s1, s1, s0
	s_mul_i32 s0, s66, s62
	s_add_u32 s6, s0, s2
	s_addc_u32 s7, s1, s63
	v_cmp_gt_i64_e32 vcc, s[6:7], v[146:147]
	v_cmp_lt_i64_e64 s[0:1], s[6:7], v[144:145]
	s_cbranch_vccnz .LBB0_557
	s_and_b32 s100, s6, 7
	s_mul_i32 s100, s100, 0x40
	s_lshr_b32 s101, s6, 3
	s_add_i32 s100, s100, s101
	s_mul_hi_u32 s101, s100, 0x8000000
	s_mul_i32 s67, s101, 0x20
	s_sub_i32 s67, s100, s67
	s_and_b32 s100, s67, 7
	s_lshl_b32 s79, s101, 3
	s_add_i32 s79, s79, s100
	s_lshr_b32 s67, s67, 3

.LBB0_652:
	s_lshr_b32 s99, s91, 2
	s_cmp_eq_u32 s99, 1
	s_cselect_b32 s98, 12, 0x7fffffff
	s_add_i32 s93, s93, 1
	s_mul_i32 s6, s93, s58
	s_mul_hi_u32 s7, s93, s59
	s_add_i32 s7, s7, s6
	s_mul_i32 s6, s93, s59
	s_add_u32 s48, s6, s2
	s_addc_u32 s49, s7, s3
	v_cmp_gt_i64_e32 vcc, s[48:49], v[146:147]
	v_cmp_lt_i64_e64 s[6:7], s[48:49], v[144:145]
	s_cbranch_vccnz .LBB0_654
	s_and_b32 s100, s48, 7
	s_mul_i32 s100, s100, 0xc0
	s_lshr_b32 s101, s48, 3
	s_add_i32 s100, s100, s101
	s_mul_hi_u32 s101, s100, 0x2aaaaab
	s_mul_i32 s40, s101, 0x60
	s_sub_i32 s40, s100, s40
	s_and_b32 s100, s40, 7
	s_lshl_b32 s42, s101, 3
	s_add_i32 s42, s42, s100
	s_lshr_b32 s40, s40, 3
	s_mov_b32 s94, s93

.LBB0_962:
	s_lshr_b32 s99, s91, 2
	s_cmp_eq_u32 s99, 1
	s_cselect_b32 s98, 12, 0x7fffffff
	s_add_i32 s66, s66, 1
	s_mul_i32 s6, s66, s59
	s_mul_hi_u32 s7, s66, s62
	s_add_i32 s7, s7, s6
	s_mul_i32 s6, s66, s62
	s_add_u32 s30, s6, s2
	s_addc_u32 s31, s7, s63
	v_cmp_gt_i64_e32 vcc, s[30:31], v[146:147]
	v_cmp_lt_i64_e64 s[6:7], s[30:31], v[144:145]
	s_cbranch_vccnz .LBB0_968
	s_and_b32 s100, s30, 7
	s_mul_i32 s100, s100, 0x40
	s_lshr_b32 s101, s30, 3
	s_add_i32 s100, s100, s101
	s_mul_hi_u32 s101, s100, 0x8000000
	s_mul_i32 s26, s101, 0x20
	s_sub_i32 s26, s100, s26
	s_and_b32 s100, s26, 7
	s_lshl_b32 s28, s101, 3
	s_add_i32 s28, s28, s100
	s_lshr_b32 s26, s26, 3

.LBB0_1056:
	s_lshr_b32 s99, s91, 2
	s_cmp_eq_u32 s99, 1
	s_cselect_b32 s98, 12, 0x7fffffff
	s_add_i32 s62, s62, 1
	s_mul_i32 s4, s62, s42
	s_mul_hi_u32 s5, s62, s43
	s_add_i32 s5, s5, s4
	s_mul_i32 s4, s62, s43
	s_add_u32 s26, s4, s2
	s_addc_u32 s27, s5, s3
	v_cmp_gt_i64_e32 vcc, s[26:27], v[146:147]
	v_cmp_lt_i64_e64 s[4:5], s[26:27], v[144:145]
	s_cbranch_vccnz .LBB0_1058
	s_and_b32 s100, s26, 7
	s_mul_i32 s100, s100, 0x160
	s_lshr_b32 s101, s26, 3
	s_add_i32 s100, s100, s101
	s_mul_hi_u32 s101, s100, 0x1745d18
	s_mul_i32 s10, s101, 0xb0
	s_sub_i32 s10, s100, s10
	s_and_b32 s100, s10, 7
	s_lshl_b32 s22, s101, 3
	s_add_i32 s22, s22, s100
	s_lshr_b32 s10, s10, 3
	s_mov_b32 s63, s62

.LBB0_1134:
	s_lshr_b32 s99, s91, 2
	s_cmp_eq_u32 s99, 1
	s_cselect_b32 s98, 40, 0x7fffffff
	s_add_i32 s58, s58, 1
	s_mul_i32 s0, s58, s53
	s_mul_hi_u32 s1, s58, s54
	s_add_i32 s1, s1, s0
	s_mul_i32 s0, s58, s54
	s_add_u32 s6, s0, s2
	s_addc_u32 s7, s1, s55
	v_cmp_gt_i64_e32 vcc, s[6:7], v[146:147]
	v_cmp_lt_i64_e64 s[0:1], s[6:7], v[144:145]
	s_cbranch_vccnz .LBB0_1140
	s_and_b32 s100, s6, 7
	s_mul_i32 s100, s100, 0x40
	s_lshr_b32 s101, s6, 3
	s_add_i32 s100, s100, s101
	s_mul_hi_u32 s101, s100, 0x8000000
	s_mul_i32 s59, s101, 0x20
	s_sub_i32 s59, s100, s59
	s_and_b32 s100, s59, 7
	s_lshl_b32 s62, s101, 3
	s_add_i32 s62, s62, s100
	s_lshr_b32 s59, s59, 3

.LBB0_1232:
	s_lshr_b32 s99, s91, 2
	s_cmp_eq_u32 s99, 1
	s_cselect_b32 s98, 12, 0x7fffffff
	s_add_i32 s58, s58, 1
	s_mul_i32 s4, s58, s42
	s_mul_hi_u32 s5, s58, s43
	s_add_i32 s5, s5, s4
	s_mul_i32 s4, s58, s43
	s_add_u32 s26, s4, s2
	s_addc_u32 s27, s5, s3
	v_cmp_gt_i64_e32 vcc, s[26:27], v[146:147]
	v_cmp_lt_i64_e64 s[4:5], s[26:27], v[144:145]
	s_cbranch_vccnz .LBB0_1234
	s_and_b32 s100, s26, 7
	s_mul_i32 s100, s100, 0xc0
	s_lshr_b32 s101, s26, 3
	s_add_i32 s100, s100, s101
	s_mul_hi_u32 s101, s100, 0x2aaaaab
	s_mul_i32 s10, s101, 0x60
	s_sub_i32 s10, s100, s10
	s_and_b32 s100, s10, 7
	s_lshl_b32 s22, s101, 3
	s_add_i32 s22, s22, s100
	s_lshr_b32 s10, s10, 3
	s_mov_b32 s59, s58

.LBB0_1550:
	s_lshr_b32 s99, s91, 2
	s_cmp_eq_u32 s99, 1
	s_cselect_b32 s98, 12, 0x7fffffff
	s_add_i32 s60, s60, 1
	s_mul_i32 s6, s60, s55
	s_mul_hi_u32 s7, s60, s56
	s_add_i32 s7, s7, s6
	s_mul_i32 s6, s60, s56
	s_add_u32 s30, s6, s2
	s_addc_u32 s31, s7, s57
	v_cmp_gt_i64_e32 vcc, s[30:31], v[144:145]
	v_cmp_lt_i64_e64 s[6:7], s[30:31], v[142:143]
	s_cbranch_vccnz .LBB0_1556
	s_and_b32 s100, s30, 7
	s_mul_i32 s100, s100, 0x40
	s_lshr_b32 s101, s30, 3
	s_add_i32 s100, s100, s101
	s_mul_hi_u32 s101, s100, 0x8000000
	s_mul_i32 s26, s101, 0x20
	s_sub_i32 s26, s100, s26
	s_and_b32 s100, s26, 7
	s_lshl_b32 s28, s101, 3
	s_add_i32 s28, s28, s100
	s_lshr_b32 s26, s26, 3

.LBB0_1644:
	s_lshr_b32 s99, s91, 2
	s_cmp_eq_u32 s99, 1
	s_cselect_b32 s98, 12, 0x7fffffff
	s_add_i32 s56, s56, 1
	s_mul_i32 s4, s56, s42
	s_mul_hi_u32 s5, s56, s43
	s_add_i32 s5, s5, s4
	s_mul_i32 s4, s56, s43
	s_add_u32 s26, s4, s2
	s_addc_u32 s27, s5, s3
	v_cmp_gt_i64_e32 vcc, s[26:27], v[144:145]
	v_cmp_lt_i64_e64 s[4:5], s[26:27], v[142:143]
	s_cbranch_vccnz .LBB0_1646
	s_and_b32 s100, s26, 7
	s_mul_i32 s100, s100, 0x160
	s_lshr_b32 s101, s26, 3
	s_add_i32 s100, s100, s101
	s_mul_hi_u32 s101, s100, 0x1745d18
	s_mul_i32 s10, s101, 0xb0
	s_sub_i32 s10, s100, s10
	s_and_b32 s100, s10, 7
	s_lshl_b32 s22, s101, 3
	s_add_i32 s22, s22, s100
	s_lshr_b32 s10, s10, 3
	s_mov_b32 s57, s56

.LBB0_1722:
	s_lshr_b32 s99, s91, 2
	s_cmp_eq_u32 s99, 1
	s_cselect_b32 s98, 40, 0x7fffffff
	s_add_i32 s54, s54, 1
	s_mul_i32 s0, s54, s49
	s_mul_hi_u32 s1, s54, s50
	s_add_i32 s1, s1, s0
	s_mul_i32 s0, s54, s50
	s_add_u32 s6, s0, s2
	s_addc_u32 s7, s1, s51
	v_cmp_gt_i64_e32 vcc, s[6:7], v[144:145]
	v_cmp_lt_i64_e64 s[0:1], s[6:7], v[142:143]
	s_cbranch_vccnz .LBB0_1728
	s_and_b32 s100, s6, 7
	s_mul_i32 s100, s100, 0x40
	s_lshr_b32 s101, s6, 3
	s_add_i32 s100, s100, s101
	s_mul_hi_u32 s101, s100, 0x8000000
	s_mul_i32 s55, s101, 0x20
	s_sub_i32 s55, s100, s55
	s_and_b32 s100, s55, 7
	s_lshl_b32 s56, s101, 3
	s_add_i32 s56, s56, s100
	s_lshr_b32 s55, s55, 3

.LBB0_1823:
	s_lshr_b32 s99, s91, 2
	s_cmp_eq_u32 s99, 1
	s_cselect_b32 s98, 12, 0x7fffffff
	s_add_i32 s63, s63, 1
	s_mul_i32 s4, s63, s48
	s_mul_hi_u32 s5, s63, s49
	s_add_i32 s5, s5, s4
	s_mul_i32 s4, s63, s49
	s_add_u32 s38, s4, s2
	s_addc_u32 s39, s5, s3
	v_cmp_gt_i64_e32 vcc, s[38:39], v[148:149]
	v_cmp_lt_i64_e64 s[4:5], s[38:39], v[146:147]
	s_cbranch_vccnz .LBB0_1825
	s_and_b32 s100, s38, 7
	s_mul_i32 s100, s100, 0xc0
	s_lshr_b32 s101, s38, 3
	s_add_i32 s100, s100, s101
	s_mul_hi_u32 s101, s100, 0x2aaaaab
	s_mul_i32 s30, s101, 0x60
	s_sub_i32 s30, s100, s30
	s_and_b32 s100, s30, 7
	s_lshl_b32 s36, s101, 3
	s_add_i32 s36, s36, s100
	s_lshr_b32 s30, s30, 3
	s_mov_b32 s64, s63

.LBB0_1994:
	s_lshr_b32 s99, s91, 2
	s_cmp_eq_u32 s99, 1
	s_cselect_b32 s98, 12, 0x7fffffff
	s_add_i32 s58, s58, 1
	s_mul_i32 s6, s58, s53
	s_mul_hi_u32 s7, s58, s54
	s_add_i32 s7, s7, s6
	s_mul_i32 s6, s58, s54
	s_add_u32 s28, s6, s2
	s_addc_u32 s29, s7, s55
	v_cmp_gt_i64_e32 vcc, s[28:29], v[144:145]
	v_cmp_lt_i64_e64 s[6:7], s[28:29], v[142:143]
	s_cbranch_vccnz .LBB0_2000
	s_and_b32 s100, s28, 7
	s_mul_i32 s100, s100, 0x40
	s_lshr_b32 s101, s28, 3
	s_add_i32 s100, s100, s101
	s_mul_hi_u32 s101, s100, 0x8000000
	s_mul_i32 s24, s101, 0x20
	s_sub_i32 s24, s100, s24
	s_and_b32 s100, s24, 7
	s_lshl_b32 s26, s101, 3
	s_add_i32 s26, s26, s100
	s_lshr_b32 s24, s24, 3

.LBB0_2088:
	s_lshr_b32 s99, s91, 2
	s_cmp_eq_u32 s99, 1
	s_cselect_b32 s98, 12, 0x7fffffff
	s_add_i32 s50, s50, 1
	s_mul_i32 s4, s50, s36
	s_mul_hi_u32 s5, s50, s37
	s_add_i32 s5, s5, s4
	s_mul_i32 s4, s50, s37
	s_add_u32 s20, s4, s2
	s_addc_u32 s21, s5, s3
	v_cmp_gt_i64_e32 vcc, s[20:21], v[144:145]
	v_cmp_lt_i64_e64 s[4:5], s[20:21], v[142:143]
	s_cbranch_vccnz .LBB0_2090
	s_and_b32 s100, s20, 7
	s_mul_i32 s100, s100, 0x160
	s_lshr_b32 s101, s20, 3
	s_add_i32 s100, s100, s101
	s_mul_hi_u32 s101, s100, 0x1745d18
	s_mul_i32 s10, s101, 0xb0
	s_sub_i32 s10, s100, s10
	s_and_b32 s100, s10, 7
	s_lshl_b32 s18, s101, 3
	s_add_i32 s18, s18, s100
	s_lshr_b32 s10, s10, 3
	s_mov_b32 s51, s50

.LBB0_2163:
	s_lshr_b32 s99, s91, 2
	s_cmp_eq_u32 s99, 1
	s_cselect_b32 s98, 40, 0x7fffffff
	s_add_i32 s45, s45, 1
	s_mul_i32 s0, s45, s48
	s_mul_hi_u32 s1, s45, s49
	s_add_i32 s1, s1, s0
	s_mul_i32 s0, s45, s49
	s_add_u32 s4, s0, s2
	s_addc_u32 s5, s1, s3
	v_cmp_gt_i64_e32 vcc, s[4:5], v[142:143]
	v_cmp_lt_i64_e64 s[0:1], s[4:5], v[140:141]
	s_cbranch_vccnz .LBB0_2169
	s_and_b32 s100, s4, 7
	s_mul_i32 s100, s100, 0x40
	s_lshr_b32 s101, s4, 3
	s_add_i32 s100, s100, s101
	s_mul_hi_u32 s101, s100, 0x8000000
	s_mul_i32 s52, s101, 0x20
	s_sub_i32 s52, s100, s52
	s_and_b32 s100, s52, 7
	s_lshl_b32 s53, s101, 3
	s_add_i32 s53, s53, s100
	s_lshr_b32 s52, s52, 3
